# plus: P0 small-cache converts batched, select scoring canonicalize removed, counted vmcnt in P2 attention loop
# speedup vs baseline: 1.1583x; 1.0130x over previous
.LBB0_91:
	v_writelane_b32 v253, s43, 60
	s_or_b64 exec, exec, s[2:3]
	s_load_dwordx2 s[20:21], s[66:67], 0x1e0
	s_ashr_i32 s53, s52, 31
	s_lshl_b64 s[0:1], s[52:53], 9
	v_mov_b32_e32 v133, 0
	v_lshl_add_u64 v[0:1], s[0:1], 0, v[132:133]
	s_waitcnt lgkmcnt(0)
	s_ashr_i32 s1, s20, 31
	s_mov_b32 s0, s20
	s_lshl_b64 s[2:3], s[0:1], 9
	s_mul_i32 s34, s20, 0xe00
	v_mov_b32_e32 v2, 0xe00
	s_mul_hi_i32 s33, s20, 0xe00
	v_mad_i64_i32 v[6:7], s[20:21], s20, v2, v[0:1]
	s_sub_u32 s38, 0xc000, s34
	s_subb_u32 s39, 0, s33
	s_lshl_b64 s[20:21], s[52:53], 12
	v_lshlrev_b32_e32 v2, 3, v132
	v_mov_b32_e32 v3, v133
	v_lshl_add_u64 v[2:3], s[20:21], 0, v[2:3]
	s_lshl_b64 s[20:21], s[52:53], 13
	v_lshlrev_b32_e32 v4, 4, v132
	v_mov_b32_e32 v5, v133
	s_mov_b64 s[40:41], 0xc000
	v_lshl_add_u64 v[4:5], s[20:21], 0, v[4:5]
	v_cmp_gt_i64_e32 vcc, s[40:41], v[6:7]
	v_lshl_add_u64 v[8:9], s[16:17], 0, v[2:3]
	s_lshl_b64 s[30:31], s[0:1], 15
	v_lshl_add_u64 v[10:11], s[12:13], 0, v[4:5]
	s_lshl_b64 s[36:37], s[0:1], 16
	s_lshl_b64 s[22:23], s[0:1], 13
	s_lshl_b64 s[20:21], s[0:1], 12
	s_mov_b32 s35, 0
	s_mov_b64 s[42:43], 0xbfff
	s_mov_b64 s[44:45], 0x66000
	s_mov_b64 s[46:47], 0xc0000
	s_cmp_eq_u32 s0, 0x100
	s_cbranch_scc0 .LBB0_93
	v_cmp_gt_u32_e32 vcc, 0xc000, v0
	s_nop 1
	s_and_saveexec_b64 s[30:31], vcc
	s_cbranch_execz .Lcv_ld_a
	global_load_dwordx4 v[8:11], v4, s[12:13]
	s_add_u32 s12, s12, 0xc0000
	s_addc_u32 s13, s13, 0
	global_load_dwordx4 v[12:15], v4, s[12:13]
	s_add_u32 s12, s12, 0xc0000
	s_addc_u32 s13, s13, 0
	global_load_dwordx4 v[16:19], v4, s[12:13]
	s_add_u32 s12, s12, 0xc0000
	s_addc_u32 s13, s13, 0
	global_load_dwordx4 v[20:23], v4, s[12:13]
	s_add_u32 s12, s12, 0xc0000
	s_addc_u32 s13, s13, 0
	global_load_dwordx4 v[24:27], v4, s[12:13]
	s_add_u32 s12, s12, 0xc0000
	s_addc_u32 s13, s13, 0
	global_load_dwordx4 v[28:31], v4, s[12:13]
	s_add_u32 s12, s12, 0xc0000
	s_addc_u32 s13, s13, 0
	global_load_dwordx4 v[32:35], v4, s[12:13]
	s_add_u32 s12, s12, 0xc0000
	s_addc_u32 s13, s13, 0
	global_load_dwordx4 v[36:39], v4, s[12:13]
	global_load_dwordx4 v[40:43], v4, s[14:15]
	s_add_u32 s14, s14, 0xc0000
	s_addc_u32 s15, s15, 0
	global_load_dwordx4 v[44:47], v4, s[14:15]
	s_add_u32 s14, s14, 0xc0000
	s_addc_u32 s15, s15, 0
	global_load_dwordx4 v[48:51], v4, s[14:15]
	s_add_u32 s14, s14, 0xc0000
	s_addc_u32 s15, s15, 0
	global_load_dwordx4 v[52:55], v4, s[14:15]
	s_add_u32 s14, s14, 0xc0000
	s_addc_u32 s15, s15, 0
	global_load_dwordx4 v[56:59], v4, s[14:15]
	s_add_u32 s14, s14, 0xc0000
	s_addc_u32 s15, s15, 0
	global_load_dwordx4 v[60:63], v4, s[14:15]
	s_add_u32 s14, s14, 0xc0000
	s_addc_u32 s15, s15, 0
	global_load_dwordx4 v[64:67], v4, s[14:15]
	s_add_u32 s14, s14, 0xc0000
	s_addc_u32 s15, s15, 0
	global_load_dwordx4 v[68:71], v4, s[14:15]
.Lcv_ld_a:
	s_or_b64 exec, exec, s[30:31]
	v_cmp_gt_u32_e32 vcc, 0x8000, v0
	s_nop 1
	s_and_saveexec_b64 s[30:31], vcc
	s_cbranch_execz .Lcv_ld_b
	global_load_dwordx4 v[72:75], v4, s[8:9]
	s_add_u32 s8, s8, 0x80000
	s_addc_u32 s9, s9, 0
	global_load_dwordx4 v[76:79], v4, s[8:9]
	s_add_u32 s8, s8, 0x80000
	s_addc_u32 s9, s9, 0
	global_load_dwordx4 v[80:83], v4, s[8:9]
	s_add_u32 s8, s8, 0x80000
	s_addc_u32 s9, s9, 0
	global_load_dwordx4 v[84:87], v4, s[8:9]
	s_add_u32 s8, s8, 0x80000
	s_addc_u32 s9, s9, 0
	global_load_dwordx4 v[88:91], v4, s[8:9]
	s_add_u32 s8, s8, 0x80000
	s_addc_u32 s9, s9, 0
	global_load_dwordx4 v[92:95], v4, s[8:9]
	s_add_u32 s8, s8, 0x80000
	s_addc_u32 s9, s9, 0
	global_load_dwordx4 v[96:99], v4, s[8:9]
	s_add_u32 s8, s8, 0x80000
	s_addc_u32 s9, s9, 0
	global_load_dwordx4 v[100:103], v4, s[8:9]
.Lcv_ld_b:
	s_or_b64 exec, exec, s[30:31]
	global_load_dwordx4 v[104:107], v4, s[10:11]
	global_load_dwordx4 v[108:111], v4, s[26:27]
	s_waitcnt vmcnt(0)
	v_cmp_gt_u32_e32 vcc, 0xc000, v0
	s_nop 1
	s_and_saveexec_b64 s[30:31], vcc
	s_cbranch_execz .Lcv_st_a
	v_cvt_pk_bf16_f32 v8, v8, v9
	v_cvt_pk_bf16_f32 v9, v10, v11
	global_store_dwordx2 v2, v[8:9], s[16:17]
	s_add_u32 s16, s16, 0x66000
	s_addc_u32 s17, s17, 0
	v_cvt_pk_bf16_f32 v12, v12, v13
	v_cvt_pk_bf16_f32 v13, v14, v15
	global_store_dwordx2 v2, v[12:13], s[16:17]
	s_add_u32 s16, s16, 0x66000
	s_addc_u32 s17, s17, 0
	v_cvt_pk_bf16_f32 v16, v16, v17
	v_cvt_pk_bf16_f32 v17, v18, v19
	global_store_dwordx2 v2, v[16:17], s[16:17]
	s_add_u32 s16, s16, 0x66000
	s_addc_u32 s17, s17, 0
	v_cvt_pk_bf16_f32 v20, v20, v21
	v_cvt_pk_bf16_f32 v21, v22, v23
	global_store_dwordx2 v2, v[20:21], s[16:17]
	s_add_u32 s16, s16, 0x66000
	s_addc_u32 s17, s17, 0
	v_cvt_pk_bf16_f32 v24, v24, v25
	v_cvt_pk_bf16_f32 v25, v26, v27
	global_store_dwordx2 v2, v[24:25], s[16:17]
	s_add_u32 s16, s16, 0x66000
	s_addc_u32 s17, s17, 0
	v_cvt_pk_bf16_f32 v28, v28, v29
	v_cvt_pk_bf16_f32 v29, v30, v31
	global_store_dwordx2 v2, v[28:29], s[16:17]
	s_add_u32 s16, s16, 0x66000
	s_addc_u32 s17, s17, 0
	v_cvt_pk_bf16_f32 v32, v32, v33
	v_cvt_pk_bf16_f32 v33, v34, v35
	global_store_dwordx2 v2, v[32:33], s[16:17]
	s_add_u32 s16, s16, 0x66000
	s_addc_u32 s17, s17, 0
	v_cvt_pk_bf16_f32 v36, v36, v37
	v_cvt_pk_bf16_f32 v37, v38, v39
	global_store_dwordx2 v2, v[36:37], s[16:17]
	v_cvt_pk_bf16_f32 v40, v40, v41
	v_cvt_pk_bf16_f32 v41, v42, v43
	global_store_dwordx2 v2, v[40:41], s[18:19]
	s_add_u32 s18, s18, 0x66000
	s_addc_u32 s19, s19, 0
	v_cvt_pk_bf16_f32 v44, v44, v45
	v_cvt_pk_bf16_f32 v45, v46, v47
	global_store_dwordx2 v2, v[44:45], s[18:19]
	s_add_u32 s18, s18, 0x66000
	s_addc_u32 s19, s19, 0
	v_cvt_pk_bf16_f32 v48, v48, v49
	v_cvt_pk_bf16_f32 v49, v50, v51
	global_store_dwordx2 v2, v[48:49], s[18:19]
	s_add_u32 s18, s18, 0x66000
	s_addc_u32 s19, s19, 0
	v_cvt_pk_bf16_f32 v52, v52, v53
	v_cvt_pk_bf16_f32 v53, v54, v55
	global_store_dwordx2 v2, v[52:53], s[18:19]
	s_add_u32 s18, s18, 0x66000
	s_addc_u32 s19, s19, 0
	v_cvt_pk_bf16_f32 v56, v56, v57
	v_cvt_pk_bf16_f32 v57, v58, v59
	global_store_dwordx2 v2, v[56:57], s[18:19]
	s_add_u32 s18, s18, 0x66000
	s_addc_u32 s19, s19, 0
	v_cvt_pk_bf16_f32 v60, v60, v61
	v_cvt_pk_bf16_f32 v61, v62, v63
	global_store_dwordx2 v2, v[60:61], s[18:19]
	s_add_u32 s18, s18, 0x66000
	s_addc_u32 s19, s19, 0
	v_cvt_pk_bf16_f32 v64, v64, v65
	v_cvt_pk_bf16_f32 v65, v66, v67
	global_store_dwordx2 v2, v[64:65], s[18:19]
	s_add_u32 s18, s18, 0x66000
	s_addc_u32 s19, s19, 0
	v_cvt_pk_bf16_f32 v68, v68, v69
	v_cvt_pk_bf16_f32 v69, v70, v71
	global_store_dwordx2 v2, v[68:69], s[18:19]
.Lcv_st_a:
	s_or_b64 exec, exec, s[30:31]
	v_cmp_gt_u32_e32 vcc, 0x8000, v0
	s_nop 1
	s_and_saveexec_b64 s[30:31], vcc
	s_cbranch_execz .Lcv_st_b
	v_cvt_pk_bf16_f32 v72, v72, v73
	v_cvt_pk_bf16_f32 v73, v74, v75
	global_store_dwordx2 v2, v[72:73], s[28:29]
	s_add_u32 s28, s28, 0x40800
	s_addc_u32 s29, s29, 0
	v_cvt_pk_bf16_f32 v76, v76, v77
	v_cvt_pk_bf16_f32 v77, v78, v79
	global_store_dwordx2 v2, v[76:77], s[28:29]
	s_add_u32 s28, s28, 0x40800
	s_addc_u32 s29, s29, 0
	v_cvt_pk_bf16_f32 v80, v80, v81
	v_cvt_pk_bf16_f32 v81, v82, v83
	global_store_dwordx2 v2, v[80:81], s[28:29]
	s_add_u32 s28, s28, 0x40800
	s_addc_u32 s29, s29, 0
	v_cvt_pk_bf16_f32 v84, v84, v85
	v_cvt_pk_bf16_f32 v85, v86, v87
	global_store_dwordx2 v2, v[84:85], s[28:29]
	s_add_u32 s28, s28, 0x40800
	s_addc_u32 s29, s29, 0
	v_cvt_pk_bf16_f32 v88, v88, v89
	v_cvt_pk_bf16_f32 v89, v90, v91
	global_store_dwordx2 v2, v[88:89], s[28:29]
	s_add_u32 s28, s28, 0x40800
	s_addc_u32 s29, s29, 0
	v_cvt_pk_bf16_f32 v92, v92, v93
	v_cvt_pk_bf16_f32 v93, v94, v95
	global_store_dwordx2 v2, v[92:93], s[28:29]
	s_add_u32 s28, s28, 0x40800
	s_addc_u32 s29, s29, 0
	v_cvt_pk_bf16_f32 v96, v96, v97
	v_cvt_pk_bf16_f32 v97, v98, v99
	global_store_dwordx2 v2, v[96:97], s[28:29]
	s_add_u32 s28, s28, 0x40800
	s_addc_u32 s29, s29, 0
	v_cvt_pk_bf16_f32 v100, v100, v101
	v_cvt_pk_bf16_f32 v101, v102, v103
	global_store_dwordx2 v2, v[100:101], s[28:29]
.Lcv_st_b:
	s_or_b64 exec, exec, s[30:31]
	v_cvt_pk_bf16_f32 v104, v104, v105
	v_cvt_pk_bf16_f32 v105, v106, v107
	global_store_dwordx2 v2, v[104:105], s[4:5]
	v_cvt_pk_bf16_f32 v108, v108, v109
	v_cvt_pk_bf16_f32 v109, v110, v111
	global_store_dwordx2 v2, v[108:109], s[6:7]
	s_mov_b64 s[0:1], exec
	s_branch .LBB0_132
	s_branch .LBB0_93

.LBB0_865:
	s_or_b64 exec, exec, s[0:1]
	s_or_b32 s1, s13, 1
	s_sub_i32 s0, s13, s17
	s_sub_i32 s3, s1, s17
	s_or_b32 s0, s0, 1
	s_sub_i32 s2, s16, s17
	s_add_i32 s1, s3, 1
	s_lshl_b32 s15, s12, 6
	s_min_i32 s21, s2, 0
	s_max_i32 s16, s0, s1
	s_cmp_lt_i32 s21, s16
	v_lshlrev_b32_e32 v66, 2, v31
	s_cbranch_scc0 .LBB0_1039
	s_lshl_b32 s8, s17, 6
	s_or_b32 s4, s11, s8
	v_readlane_b32 s24, v254, 25
	s_mul_i32 s6, s4, 0x300
	v_readlane_b32 s26, v254, 27
	v_readlane_b32 s27, v254, 28
	s_add_u32 s4, s26, s6
	s_addc_u32 s5, s27, 0
	s_lshl_b32 s7, s15, 1
	s_add_u32 s4, s4, s7
	s_addc_u32 s5, s5, 0
	v_readlane_b32 s12, v254, 23
	v_readlane_b32 s13, v254, 24
	s_add_u32 s6, s12, s6
	s_addc_u32 s9, s13, 0
	s_add_u32 s6, s6, s7
	s_addc_u32 s7, s9, 0
	s_sub_i32 s10, s10, s8
	v_ashrrev_i32_e32 v45, 3, v18
	v_lshlrev_b32_e32 v8, 4, v18
	s_lshl_b32 s18, s21, 6
	s_add_i32 s17, s10, 0x7f
	v_and_b32_e32 v16, 0x70, v8
	v_add3_u32 v8, s18, 64, v45
	v_add_u32_e32 v19, s18, v45
	v_min_i32_e32 v12, s17, v8
	v_mov_b64_e32 v[20:21], s[6:7]
	s_movk_i32 s11, 0x300
	v_mov_b64_e32 v[24:25], s[4:5]
	v_min_i32_e32 v19, s17, v19
	v_mad_i64_i32 v[8:9], s[8:9], v12, s11, v[20:21]
	v_mad_i64_i32 v[12:13], s[8:9], v12, s11, v[24:25]
	v_mad_i64_i32 v[20:21], s[8:9], v19, s11, v[20:21]
	v_mad_i64_i32 v[24:25], s[8:9], v19, s11, v[24:25]
	v_lshl_add_u64 v[8:9], v[8:9], 0, v[16:17]
	v_lshl_add_u64 v[12:13], v[12:13], 0, v[16:17]
	v_lshl_add_u64 v[20:21], v[20:21], 0, v[16:17]
	v_lshl_add_u64 v[24:25], v[24:25], 0, v[16:17]
	global_load_dwordx4 v[8:11], v[8:9], off
	v_lshl_add_u64 v[46:47], s[4:5], 0, v[16:17]
	global_load_dwordx4 v[12:15], v[12:13], off
	v_or_b32_e32 v30, v30, v29
	global_load_dwordx4 v[20:23], v[20:21], off
	s_movk_i32 s4, 0x7f
	global_load_dwordx4 v[24:27], v[24:25], off
	v_cmp_lt_i32_e64 s[8:9], s4, v30
	v_mov_b32_e32 v30, s2
	s_movk_i32 s2, 0x100
	v_cmp_gt_u32_e32 vcc, s2, v18
	s_lshl_b32 s3, s3, 6
	v_mov_b32_e32 v18, s1
	v_cndmask_b32_e64 v68, v30, 0, vcc
	v_mov_b32_e32 v30, s0
	v_cndmask_b32_e32 v69, v18, v30, vcc
	v_mov_b32_e32 v18, s3
	v_mov_b32_e32 v30, s10
	v_lshlrev_b32_e32 v19, 3, v31
	v_lshrrev_b32_e32 v31, 2, v28
	v_cndmask_b32_e32 v18, v18, v30, vcc
	s_movk_i32 s0, 0xa0
	v_or_b32_e32 v31, v66, v31
	v_lshl_add_u64 v[48:49], s[6:7], 0, v[16:17]
	v_mad_u64_u32 v[50:51], s[0:1], v45, s0, v[16:17]
	v_add3_u32 v16, v18, v29, v28
	v_mul_u32_u24_e32 v31, 0xa0, v31
	v_lshlrev_b32_e32 v32, 3, v28
	v_sub_u32_e32 v16, v16, v66
	v_and_or_b32 v31, v32, 24, v31
	v_lshlrev_b32_e32 v51, 1, v19
	v_subrev_u32_e32 v16, s18, v16
	v_mov_b32_e32 v18, v17
	v_mov_b32_e32 v19, v17
	v_add_u32_e32 v67, 0x2800, v31
	v_mul_u32_u24_e32 v80, 0xa0, v28
	v_add_u32_e32 v81, 0x3c00, v31
	v_subrev_u32_e32 v82, 51, v16
	v_mov_b32_e32 v16, v17
	v_mov_b64_e32 v[34:35], v[18:19]
	v_mov_b64_e32 v[42:43], v[18:19]
	v_mov_b64_e32 v[38:39], v[18:19]
	v_mov_b64_e32 v[30:31], v[18:19]
	s_add_i32 s19, s10, 0x80
	v_mov_b32_e32 v84, 0xff800000
	v_mov_b32_e32 v83, 0
	v_mov_b64_e32 v[32:33], v[16:17]
	v_mov_b64_e32 v[40:41], v[16:17]
	v_mov_b64_e32 v[36:37], v[16:17]
	v_mov_b64_e32 v[28:29], v[16:17]
	v_readlane_b32 s25, v254, 26
	s_waitcnt vmcnt(0)
.LBB0_867:
	s_add_i32 s20, s21, 2
	s_cmp_ge_i32 s20, s16
	s_cselect_b64 s[10:11], -1, 0
	s_and_b64 vcc, exec, s[10:11]
	s_waitcnt lgkmcnt(0)
	s_barrier
	s_add_i32 s1, s21, 1
	s_cmp_lt_i32 s1, s16
	s_cbranch_scc0 .Lp2a_w0
	s_waitcnt vmcnt(2)
	s_branch .Lp2a_wd

.Lp2a_wd:
	ds_write_b128 v50, v[24:27]
	ds_write_b128 v50, v[20:23] offset:10240
	s_waitcnt lgkmcnt(0)
	s_barrier
	s_cbranch_vccnz .LBB0_869
	v_add_u32_e32 v16, s18, v45
	v_add_u32_e32 v16, 0x80, v16
	v_min_i32_e32 v16, s17, v16
	s_movk_i32 s2, 0x300
	v_mad_i64_i32 v[18:19], s[0:1], v16, s2, v[46:47]
	global_load_dwordx4 v[24:27], v[18:19], off
	v_mad_i64_i32 v[18:19], s[0:1], v16, s2, v[48:49]
	global_load_dwordx4 v[20:23], v[18:19], off

.LBB0_875:
	s_add_i32 s1, s21, 2
	s_cmp_lt_i32 s1, s16
	s_cbranch_scc0 .Lp2b_w0
	s_waitcnt vmcnt(2)
	s_branch .Lp2b_wd
.Lp2b_w0:
	s_waitcnt vmcnt(0)
.Lp2b_wd:
	s_add_i32 s1, s21, 3
	s_cmp_ge_i32 s1, s16
	s_barrier
	ds_write_b128 v50, v[12:15]
	ds_write_b128 v50, v[8:11] offset:10240
	s_waitcnt lgkmcnt(0)
	s_barrier
	s_cbranch_scc1 .LBB0_877
	v_add_u32_e32 v8, s18, v45
	v_add_u32_e32 v8, 0xc0, v8
	v_min_i32_e32 v10, s17, v8
	s_movk_i32 s1, 0x300
	v_mad_i64_i32 v[8:9], s[2:3], v10, s1, v[46:47]
	global_load_dwordx4 v[12:15], v[8:9], off
	v_mad_i64_i32 v[8:9], s[2:3], v10, s1, v[48:49]
	global_load_dwordx4 v[8:11], v[8:9], off

.LBB0_888:
	s_nop 1
	v_min_u32_e32 v0, s7, v49
	v_lshlrev_b32_e32 v16, 6, v0
	v_lshl_add_u64 v[52:53], v[44:45], 0, v[16:17]
	global_load_dwordx4 v[0:3], v[52:53], off
	v_cmp_gt_u32_e32 vcc, s72, v49
	global_load_dwordx4 v[52:55], v[52:53], off offset:32
	s_waitcnt vmcnt(1)
	v_mfma_f32_32x32x16_bf16 v[0:15], v[18:21], v[0:3], 0
	s_waitcnt vmcnt(0)
	v_mfma_f32_32x32x16_bf16 v[0:15], v[22:25], v[52:55], v[0:15]
	s_and_saveexec_b64 s[4:5], vcc
	s_cbranch_execz .LBB0_887
	s_nop 9
	v_max_f32_e32 v0, 0, v0
	v_max_f32_e32 v1, 0, v1
	v_max_f32_e32 v8, 0, v8
	v_max_f32_e32 v9, 0, v9
	v_pk_mul_f32 v[0:1], v[38:39], v[0:1]
	v_pk_mul_f32 v[8:9], v[30:31], v[8:9]
	v_max_f32_e32 v2, 0, v2
	v_max_f32_e32 v3, 0, v3
	v_max_f32_e32 v10, 0, v10
	v_max_f32_e32 v11, 0, v11
	v_mov_b32_e32 v52, v8
	v_mov_b32_e32 v53, v0
	v_pk_mul_f32 v[2:3], v[40:41], v[2:3]
	v_pk_mul_f32 v[10:11], v[32:33], v[10:11]
	v_pk_add_f32 v[52:53], v[52:53], 0 op_sel_hi:[1,0]
	v_mov_b32_e32 v0, v9
	v_max_f32_e32 v4, 0, v4
	v_max_f32_e32 v5, 0, v5
	v_max_f32_e32 v12, 0, v12
	v_max_f32_e32 v13, 0, v13
	v_pk_add_f32 v[0:1], v[0:1], v[52:53]
	v_mov_b32_e32 v8, v10
	v_mov_b32_e32 v9, v2
	v_pk_mul_f32 v[4:5], v[34:35], v[4:5]
	v_pk_mul_f32 v[12:13], v[26:27], v[12:13]
	v_pk_add_f32 v[0:1], v[8:9], v[0:1]
	v_mov_b32_e32 v2, v11
	v_max_f32_e32 v6, 0, v6
	v_max_f32_e32 v7, 0, v7
	v_max_f32_e32 v14, 0, v14
	v_max_f32_e32 v15, 0, v15
	v_pk_add_f32 v[0:1], v[2:3], v[0:1]
	v_mov_b32_e32 v2, v12
	v_mov_b32_e32 v3, v4
	v_pk_mul_f32 v[6:7], v[36:37], v[6:7]
	v_pk_mul_f32 v[14:15], v[28:29], v[14:15]
	v_pk_add_f32 v[0:1], v[2:3], v[0:1]
	v_mov_b32_e32 v4, v13
	v_pk_add_f32 v[0:1], v[4:5], v[0:1]
	v_mov_b32_e32 v2, v14
	v_mov_b32_e32 v3, v6
	v_pk_add_f32 v[0:1], v[2:3], v[0:1]
	v_mov_b32_e32 v6, v15
	v_pk_add_f32 v[0:1], v[6:7], v[0:1]
	s_nop 0
	v_or_b32_e32 v2, 0x80000000, v1
	v_not_b32_e32 v3, v1
	v_cmp_gt_i32_e32 vcc, 0, v1
	s_nop 1
	v_cndmask_b32_e32 v1, v2, v3, vcc
	v_or_b32_e32 v2, 0x80000000, v0
	v_not_b32_e32 v3, v0
	v_cmp_gt_i32_e32 vcc, 0, v0
	s_nop 1
	v_cndmask_b32_e32 v0, v2, v3, vcc
	ds_write2st64_b32 v48, v1, v0 offset1:65
	s_branch .LBB0_887
